# attention block diamonds: wave-uniform branch test shortened (7.12): scc branch goes straight to the plain path, masked path ends with s_branch; on v91
# baseline (speedup 1.0000x reference)
.LBB0_331:
	s_add_i32 s13, 0, 0x12000
	v_mov_b32_e32 v0, s13
	s_waitcnt lgkmcnt(0)
	s_barrier
	ds_read_b32 v152, v0
	ds_read_b128 v[172:175], v237
	ds_read_b128 v[176:179], v237 offset:64
	ds_read_b128 v[180:183], v237 offset:2304
	ds_read_b128 v[184:187], v237 offset:2368
	ds_read_b64_tr_b16 v[156:157], v238 offset:9216
	ds_read_b64_tr_b16 v[158:159], v239 offset:9216
	ds_read_b64_tr_b16 v[160:161], v238 offset:9248
	ds_read_b64_tr_b16 v[164:165], v238 offset:9280
	ds_read_b64_tr_b16 v[168:169], v238 offset:9312
	ds_read_b64_tr_b16 v[162:163], v239 offset:9248
	ds_read_b64_tr_b16 v[166:167], v239 offset:9280
	ds_read_b64_tr_b16 v[170:171], v239 offset:9312
	s_lshl_b32 s20, s18, 1
	s_sub_i32 s21, s20, s85
	s_cmp_lt_u32 s21, 9
	s_waitcnt lgkmcnt(12)
	v_mov_b32_e32 v153, v152
	v_mov_b32_e32 v154, v152
	s_cselect_b64 s[66:67], -1, 0
	s_cmp_gt_u32 s21, 8
	v_mov_b32_e32 v155, v152
	s_cbranch_scc1 .LBB0_337
	s_cmp_lt_u32 s21, 6
	s_mov_b64 s[4:5], -1
	s_cbranch_scc1 .Latt_plain_334
	v_lshl_add_u32 v0, s21, 6, v233
	v_max_i32_e32 v188, 0xffffffef, v0
	v_max_i32_e32 v2, 0, v0
	v_lshl_add_u32 v193, v188, 2, s13
	v_max_i32_e32 v188, 0xffffffee, v0
	v_lshl_add_u32 v2, v2, 2, s13
	v_max_i32_e32 v3, -1, v0
	v_max_i32_e32 v5, -2, v0
	v_max_i32_e32 v6, -3, v0
	v_max_i32_e32 v7, -16, v0
	v_lshl_add_u32 v194, v188, 2, s13
	v_max_i32_e32 v0, 0xffffffed, v0
	v_lshl_add_u32 v3, v3, 2, s13
	v_lshl_add_u32 v5, v5, 2, s13
	v_lshl_add_u32 v6, v6, 2, s13
	v_lshl_add_u32 v7, v7, 2, s13
	v_lshl_add_u32 v0, v0, 2, s13
	ds_read_b32 v188, v2
	ds_read_b32 v189, v3 offset:4
	ds_read_b32 v190, v5 offset:8
	ds_read_b32 v191, v6 offset:12
	ds_read_b32 v192, v7 offset:64
	ds_read_b32 v193, v193 offset:68
	ds_read_b32 v194, v194 offset:72
	ds_read_b32 v195, v0 offset:76
	s_waitcnt lgkmcnt(4)
	v_mfma_f32_16x16x32_bf16 v[188:191], v[172:175], v[64:67], v[188:191]
	s_mov_b64 s[4:5], 0
	s_waitcnt lgkmcnt(0)
	v_mfma_f32_16x16x32_bf16 v[192:195], v[180:183], v[64:67], v[192:195]
	s_nop 0
	v_mfma_f32_16x16x32_bf16 v[188:191], v[176:179], v[68:71], v[188:191]
	v_mfma_f32_16x16x32_bf16 v[192:195], v[184:187], v[68:71], v[192:195]
	s_branch .LBB0_336
.Latt_plain_334:
	s_waitcnt lgkmcnt(11)
	v_mfma_f32_16x16x32_bf16 v[188:191], v[172:175], v[64:67], v[152:155]
	s_waitcnt lgkmcnt(9)
	v_mfma_f32_16x16x32_bf16 v[192:195], v[180:183], v[64:67], v[152:155]
	s_nop 0
	v_mfma_f32_16x16x32_bf16 v[188:191], v[176:179], v[68:71], v[188:191]
	s_waitcnt lgkmcnt(8)
	v_mfma_f32_16x16x32_bf16 v[192:195], v[184:187], v[68:71], v[192:195]

.LBB0_337:
	s_add_i32 s14, s21, -2
	s_cmp_lt_u32 s14, 9
	s_cselect_b64 s[68:69], -1, 0
	s_cmp_gt_u32 s14, 8
	s_cbranch_scc1 .LBB0_343
	s_cmp_lt_u32 s14, 6
	s_mov_b64 s[4:5], -1
	s_cbranch_scc1 .Latt_plain_340
	v_lshl_add_u32 v0, s14, 6, v233
	v_max_i32_e32 v188, 0xffffffef, v0
	v_max_i32_e32 v2, 0, v0
	v_lshl_add_u32 v193, v188, 2, s13
	v_max_i32_e32 v188, 0xffffffee, v0
	v_lshl_add_u32 v2, v2, 2, s13
	v_max_i32_e32 v3, -1, v0
	v_max_i32_e32 v5, -2, v0
	v_max_i32_e32 v6, -3, v0
	v_max_i32_e32 v7, -16, v0
	v_lshl_add_u32 v194, v188, 2, s13
	v_max_i32_e32 v0, 0xffffffed, v0
	v_lshl_add_u32 v3, v3, 2, s13
	v_lshl_add_u32 v5, v5, 2, s13
	v_lshl_add_u32 v6, v6, 2, s13
	v_lshl_add_u32 v7, v7, 2, s13
	v_lshl_add_u32 v0, v0, 2, s13
	ds_read_b32 v188, v2
	ds_read_b32 v189, v3 offset:4
	ds_read_b32 v190, v5 offset:8
	ds_read_b32 v191, v6 offset:12
	ds_read_b32 v192, v7 offset:64
	ds_read_b32 v193, v193 offset:68
	ds_read_b32 v194, v194 offset:72
	ds_read_b32 v195, v0 offset:76
	s_waitcnt lgkmcnt(4)
	v_mfma_f32_16x16x32_bf16 v[188:191], v[172:175], v[76:79], v[188:191]
	s_mov_b64 s[4:5], 0
	s_waitcnt lgkmcnt(0)
	v_mfma_f32_16x16x32_bf16 v[192:195], v[180:183], v[76:79], v[192:195]
	s_nop 0
	v_mfma_f32_16x16x32_bf16 v[188:191], v[176:179], v[80:83], v[188:191]
	v_mfma_f32_16x16x32_bf16 v[192:195], v[184:187], v[80:83], v[192:195]
	s_branch .LBB0_342
.Latt_plain_340:
	s_waitcnt lgkmcnt(11)
	v_mfma_f32_16x16x32_bf16 v[188:191], v[172:175], v[76:79], v[152:155]
	s_waitcnt lgkmcnt(9)
	v_mfma_f32_16x16x32_bf16 v[192:195], v[180:183], v[76:79], v[152:155]
	s_nop 0
	v_mfma_f32_16x16x32_bf16 v[188:191], v[176:179], v[80:83], v[188:191]
	s_waitcnt lgkmcnt(8)
	v_mfma_f32_16x16x32_bf16 v[192:195], v[184:187], v[80:83], v[192:195]

.LBB0_343:
	s_add_i32 s15, s21, -4
	s_cmp_lt_u32 s15, 9
	s_cselect_b64 s[70:71], -1, 0
	s_cmp_gt_u32 s15, 8
	s_cbranch_scc1 .LBB0_349
	s_cmp_lt_u32 s15, 6
	s_mov_b64 s[4:5], -1
	s_cbranch_scc1 .Latt_plain_346
	v_lshl_add_u32 v0, s15, 6, v233
	v_max_i32_e32 v188, 0xffffffef, v0
	v_max_i32_e32 v2, 0, v0
	v_lshl_add_u32 v193, v188, 2, s13
	v_max_i32_e32 v188, 0xffffffee, v0
	v_lshl_add_u32 v2, v2, 2, s13
	v_max_i32_e32 v3, -1, v0
	v_max_i32_e32 v5, -2, v0
	v_max_i32_e32 v6, -3, v0
	v_max_i32_e32 v7, -16, v0
	v_lshl_add_u32 v194, v188, 2, s13
	v_max_i32_e32 v0, 0xffffffed, v0
	v_lshl_add_u32 v3, v3, 2, s13
	v_lshl_add_u32 v5, v5, 2, s13
	v_lshl_add_u32 v6, v6, 2, s13
	v_lshl_add_u32 v7, v7, 2, s13
	v_lshl_add_u32 v0, v0, 2, s13
	ds_read_b32 v188, v2
	ds_read_b32 v189, v3 offset:4
	ds_read_b32 v190, v5 offset:8
	ds_read_b32 v191, v6 offset:12
	ds_read_b32 v192, v7 offset:64
	ds_read_b32 v193, v193 offset:68
	ds_read_b32 v194, v194 offset:72
	ds_read_b32 v195, v0 offset:76
	s_waitcnt lgkmcnt(4)
	v_mfma_f32_16x16x32_bf16 v[188:191], v[172:175], v[84:87], v[188:191]
	s_mov_b64 s[4:5], 0
	s_waitcnt lgkmcnt(0)
	v_mfma_f32_16x16x32_bf16 v[192:195], v[180:183], v[84:87], v[192:195]
	s_nop 0
	v_mfma_f32_16x16x32_bf16 v[188:191], v[176:179], v[88:91], v[188:191]
	v_mfma_f32_16x16x32_bf16 v[192:195], v[184:187], v[88:91], v[192:195]
	s_branch .LBB0_348
.Latt_plain_346:
	s_waitcnt lgkmcnt(11)
	v_mfma_f32_16x16x32_bf16 v[188:191], v[172:175], v[84:87], v[152:155]
	s_waitcnt lgkmcnt(9)
	v_mfma_f32_16x16x32_bf16 v[192:195], v[180:183], v[84:87], v[152:155]
	s_nop 0
	v_mfma_f32_16x16x32_bf16 v[188:191], v[176:179], v[88:91], v[188:191]
	s_waitcnt lgkmcnt(8)
	v_mfma_f32_16x16x32_bf16 v[192:195], v[184:187], v[88:91], v[192:195]

.LBB0_349:
	s_add_i32 s17, s21, -6
	s_cmp_lt_u32 s17, 9
	s_cselect_b64 s[72:73], -1, 0
	s_cmp_gt_u32 s17, 8
	s_cbranch_scc1 .LBB0_355
	s_cmp_lt_u32 s17, 6
	s_mov_b64 s[4:5], -1
	s_cbranch_scc1 .Latt_plain_352
	v_lshl_add_u32 v0, s17, 6, v233
	v_max_i32_e32 v188, 0xffffffef, v0
	v_max_i32_e32 v2, 0, v0
	v_lshl_add_u32 v193, v188, 2, s13
	v_max_i32_e32 v188, 0xffffffee, v0
	v_lshl_add_u32 v2, v2, 2, s13
	v_max_i32_e32 v3, -1, v0
	v_max_i32_e32 v5, -2, v0
	v_max_i32_e32 v6, -3, v0
	v_max_i32_e32 v7, -16, v0
	v_lshl_add_u32 v194, v188, 2, s13
	v_max_i32_e32 v0, 0xffffffed, v0
	v_lshl_add_u32 v3, v3, 2, s13
	v_lshl_add_u32 v5, v5, 2, s13
	v_lshl_add_u32 v6, v6, 2, s13
	v_lshl_add_u32 v7, v7, 2, s13
	v_lshl_add_u32 v0, v0, 2, s13
	ds_read_b32 v188, v2
	ds_read_b32 v189, v3 offset:4
	ds_read_b32 v190, v5 offset:8
	ds_read_b32 v191, v6 offset:12
	ds_read_b32 v192, v7 offset:64
	ds_read_b32 v193, v193 offset:68
	ds_read_b32 v194, v194 offset:72
	ds_read_b32 v195, v0 offset:76
	s_waitcnt lgkmcnt(4)
	v_mfma_f32_16x16x32_bf16 v[188:191], v[172:175], v[92:95], v[188:191]
	s_mov_b64 s[4:5], 0
	s_waitcnt lgkmcnt(0)
	v_mfma_f32_16x16x32_bf16 v[192:195], v[180:183], v[92:95], v[192:195]
	s_nop 0
	v_mfma_f32_16x16x32_bf16 v[188:191], v[176:179], v[96:99], v[188:191]
	v_mfma_f32_16x16x32_bf16 v[192:195], v[184:187], v[96:99], v[192:195]
	s_branch .LBB0_354
.Latt_plain_352:
	s_waitcnt lgkmcnt(11)
	v_mfma_f32_16x16x32_bf16 v[172:175], v[172:175], v[92:95], v[152:155]
	s_waitcnt lgkmcnt(10)
	v_mfma_f32_16x16x32_bf16 v[188:191], v[176:179], v[96:99], v[172:175]
	s_waitcnt lgkmcnt(9)
	v_mfma_f32_16x16x32_bf16 v[172:175], v[180:183], v[92:95], v[152:155]
	s_waitcnt lgkmcnt(8)
	v_mfma_f32_16x16x32_bf16 v[192:195], v[184:187], v[96:99], v[172:175]

.LBB0_467:
	s_cmp_lt_u32 s21, 6
	s_mov_b64 s[4:5], -1
	s_cbranch_scc1 .Latt_plain_469
	v_lshl_add_u32 v0, s21, 6, v234
	v_max_i32_e32 v188, 0xffffffef, v0
	v_max_i32_e32 v2, 0, v0
	v_lshl_add_u32 v193, v188, 2, s13
	v_max_i32_e32 v188, 0xffffffee, v0
	v_lshl_add_u32 v2, v2, 2, s13
	v_max_i32_e32 v3, -1, v0
	v_max_i32_e32 v5, -2, v0
	v_max_i32_e32 v6, -3, v0
	v_max_i32_e32 v7, -16, v0
	v_lshl_add_u32 v194, v188, 2, s13
	v_max_i32_e32 v0, 0xffffffed, v0
	v_lshl_add_u32 v3, v3, 2, s13
	v_lshl_add_u32 v5, v5, 2, s13
	v_lshl_add_u32 v6, v6, 2, s13
	v_lshl_add_u32 v7, v7, 2, s13
	v_lshl_add_u32 v0, v0, 2, s13
	ds_read_b32 v188, v2
	ds_read_b32 v189, v3 offset:4
	ds_read_b32 v190, v5 offset:8
	ds_read_b32 v191, v6 offset:12
	ds_read_b32 v192, v7 offset:64
	ds_read_b32 v193, v193 offset:68
	ds_read_b32 v194, v194 offset:72
	ds_read_b32 v195, v0 offset:76
	s_waitcnt lgkmcnt(4)
	v_mfma_f32_16x16x32_bf16 v[188:191], v[172:175], v[76:79], v[188:191]
	s_mov_b64 s[4:5], 0
	s_waitcnt lgkmcnt(0)
	v_mfma_f32_16x16x32_bf16 v[192:195], v[180:183], v[76:79], v[192:195]
	s_nop 0
	v_mfma_f32_16x16x32_bf16 v[188:191], v[176:179], v[80:83], v[188:191]
	v_mfma_f32_16x16x32_bf16 v[192:195], v[184:187], v[80:83], v[192:195]
	s_branch .LBB0_471

.LBB0_472:
	s_cmp_lt_u32 s15, 6
	s_mov_b64 s[4:5], -1
	s_cbranch_scc1 .Latt_plain_474
	v_lshl_add_u32 v0, s15, 6, v234
	v_max_i32_e32 v188, 0xffffffef, v0
	v_max_i32_e32 v2, 0, v0
	v_lshl_add_u32 v193, v188, 2, s13
	v_max_i32_e32 v188, 0xffffffee, v0
	v_lshl_add_u32 v2, v2, 2, s13
	v_max_i32_e32 v3, -1, v0
	v_max_i32_e32 v5, -2, v0
	v_max_i32_e32 v6, -3, v0
	v_max_i32_e32 v7, -16, v0
	v_lshl_add_u32 v194, v188, 2, s13
	v_max_i32_e32 v0, 0xffffffed, v0
	v_lshl_add_u32 v3, v3, 2, s13
	v_lshl_add_u32 v5, v5, 2, s13
	v_lshl_add_u32 v6, v6, 2, s13
	v_lshl_add_u32 v7, v7, 2, s13
	v_lshl_add_u32 v0, v0, 2, s13
	ds_read_b32 v188, v2
	ds_read_b32 v189, v3 offset:4
	ds_read_b32 v190, v5 offset:8
	ds_read_b32 v191, v6 offset:12
	ds_read_b32 v192, v7 offset:64
	ds_read_b32 v193, v193 offset:68
	ds_read_b32 v194, v194 offset:72
	ds_read_b32 v195, v0 offset:76
	s_waitcnt lgkmcnt(4)
	v_mfma_f32_16x16x32_bf16 v[188:191], v[172:175], v[84:87], v[188:191]
	s_mov_b64 s[4:5], 0
	s_waitcnt lgkmcnt(0)
	v_mfma_f32_16x16x32_bf16 v[192:195], v[180:183], v[84:87], v[192:195]
	s_nop 0
	v_mfma_f32_16x16x32_bf16 v[188:191], v[176:179], v[88:91], v[188:191]
	v_mfma_f32_16x16x32_bf16 v[192:195], v[184:187], v[88:91], v[192:195]
	s_branch .LBB0_476

.LBB0_477:
	s_cmp_lt_u32 s17, 6
	s_mov_b64 s[4:5], -1
	s_cbranch_scc1 .Latt_plain_479
	v_lshl_add_u32 v0, s17, 6, v234
	v_max_i32_e32 v188, 0xffffffef, v0
	v_max_i32_e32 v2, 0, v0
	v_lshl_add_u32 v193, v188, 2, s13
	v_max_i32_e32 v188, 0xffffffee, v0
	v_lshl_add_u32 v2, v2, 2, s13
	v_max_i32_e32 v3, -1, v0
	v_max_i32_e32 v5, -2, v0
	v_max_i32_e32 v6, -3, v0
	v_max_i32_e32 v7, -16, v0
	v_lshl_add_u32 v194, v188, 2, s13
	v_max_i32_e32 v0, 0xffffffed, v0
	v_lshl_add_u32 v3, v3, 2, s13
	v_lshl_add_u32 v5, v5, 2, s13
	v_lshl_add_u32 v6, v6, 2, s13
	v_lshl_add_u32 v7, v7, 2, s13
	v_lshl_add_u32 v0, v0, 2, s13
	ds_read_b32 v188, v2
	ds_read_b32 v189, v3 offset:4
	ds_read_b32 v190, v5 offset:8
	ds_read_b32 v191, v6 offset:12
	ds_read_b32 v192, v7 offset:64
	ds_read_b32 v193, v193 offset:68
	ds_read_b32 v194, v194 offset:72
	ds_read_b32 v195, v0 offset:76
	s_waitcnt lgkmcnt(4)
	v_mfma_f32_16x16x32_bf16 v[188:191], v[172:175], v[92:95], v[188:191]
	s_mov_b64 s[4:5], 0
	s_waitcnt lgkmcnt(0)
	v_mfma_f32_16x16x32_bf16 v[192:195], v[180:183], v[92:95], v[192:195]
	s_nop 0
	v_mfma_f32_16x16x32_bf16 v[188:191], v[176:179], v[96:99], v[188:191]
	v_mfma_f32_16x16x32_bf16 v[192:195], v[184:187], v[96:99], v[192:195]
	s_branch .LBB0_481

.LBB0_511:
	s_cmp_lt_u32 s14, 6
	s_mov_b64 s[4:5], -1
	s_cbranch_scc1 .Latt_plain_513
	v_lshl_add_u32 v0, s14, 6, v234
	v_max_i32_e32 v188, 0xffffffef, v0
	v_max_i32_e32 v2, 0, v0
	v_lshl_add_u32 v193, v188, 2, s13
	v_max_i32_e32 v188, 0xffffffee, v0
	v_lshl_add_u32 v2, v2, 2, s13
	v_max_i32_e32 v3, -1, v0
	v_max_i32_e32 v5, -2, v0
	v_max_i32_e32 v6, -3, v0
	v_max_i32_e32 v7, -16, v0
	v_lshl_add_u32 v194, v188, 2, s13
	v_max_i32_e32 v0, 0xffffffed, v0
	v_lshl_add_u32 v3, v3, 2, s13
	v_lshl_add_u32 v5, v5, 2, s13
	v_lshl_add_u32 v6, v6, 2, s13
	v_lshl_add_u32 v7, v7, 2, s13
	v_lshl_add_u32 v0, v0, 2, s13
	ds_read_b32 v188, v2
	ds_read_b32 v189, v3 offset:4
	ds_read_b32 v190, v5 offset:8
	ds_read_b32 v191, v6 offset:12
	ds_read_b32 v192, v7 offset:64
	ds_read_b32 v193, v193 offset:68
	ds_read_b32 v194, v194 offset:72
	ds_read_b32 v195, v0 offset:76
	s_waitcnt lgkmcnt(4)
	v_mfma_f32_16x16x32_bf16 v[188:191], v[172:175], v[64:67], v[188:191]
	s_mov_b64 s[4:5], 0
	s_waitcnt lgkmcnt(0)
	v_mfma_f32_16x16x32_bf16 v[192:195], v[180:183], v[64:67], v[192:195]
	s_nop 0
	v_mfma_f32_16x16x32_bf16 v[188:191], v[176:179], v[68:71], v[188:191]
	v_mfma_f32_16x16x32_bf16 v[192:195], v[184:187], v[68:71], v[192:195]
	s_branch .LBB0_515

.LBB0_516:
	s_cmp_lt_u32 s15, 6
	s_mov_b64 s[4:5], -1
	s_cbranch_scc1 .Latt_plain_518
	v_lshl_add_u32 v0, s15, 6, v234
	v_max_i32_e32 v188, 0xffffffef, v0
	v_max_i32_e32 v2, 0, v0
	v_lshl_add_u32 v193, v188, 2, s13
	v_max_i32_e32 v188, 0xffffffee, v0
	v_lshl_add_u32 v2, v2, 2, s13
	v_max_i32_e32 v3, -1, v0
	v_max_i32_e32 v5, -2, v0
	v_max_i32_e32 v6, -3, v0
	v_max_i32_e32 v7, -16, v0
	v_lshl_add_u32 v194, v188, 2, s13
	v_max_i32_e32 v0, 0xffffffed, v0
	v_lshl_add_u32 v3, v3, 2, s13
	v_lshl_add_u32 v5, v5, 2, s13
	v_lshl_add_u32 v6, v6, 2, s13
	v_lshl_add_u32 v7, v7, 2, s13
	v_lshl_add_u32 v0, v0, 2, s13
	ds_read_b32 v188, v2
	ds_read_b32 v189, v3 offset:4
	ds_read_b32 v190, v5 offset:8
	ds_read_b32 v191, v6 offset:12
	ds_read_b32 v192, v7 offset:64
	ds_read_b32 v193, v193 offset:68
	ds_read_b32 v194, v194 offset:72
	ds_read_b32 v195, v0 offset:76
	s_waitcnt lgkmcnt(4)
	v_mfma_f32_16x16x32_bf16 v[188:191], v[172:175], v[76:79], v[188:191]
	s_mov_b64 s[4:5], 0
	s_waitcnt lgkmcnt(0)
	v_mfma_f32_16x16x32_bf16 v[192:195], v[180:183], v[76:79], v[192:195]
	s_nop 0
	v_mfma_f32_16x16x32_bf16 v[188:191], v[176:179], v[80:83], v[188:191]
	v_mfma_f32_16x16x32_bf16 v[192:195], v[184:187], v[80:83], v[192:195]
	s_branch .LBB0_520

.LBB0_521:
	s_cmp_lt_u32 s17, 6
	s_mov_b64 s[4:5], -1
	s_cbranch_scc1 .Latt_plain_523
	v_lshl_add_u32 v0, s17, 6, v234
	v_max_i32_e32 v188, 0xffffffef, v0
	v_max_i32_e32 v2, 0, v0
	v_lshl_add_u32 v193, v188, 2, s13
	v_max_i32_e32 v188, 0xffffffee, v0
	v_lshl_add_u32 v2, v2, 2, s13
	v_max_i32_e32 v3, -1, v0
	v_max_i32_e32 v5, -2, v0
	v_max_i32_e32 v6, -3, v0
	v_max_i32_e32 v7, -16, v0
	v_lshl_add_u32 v194, v188, 2, s13
	v_max_i32_e32 v0, 0xffffffed, v0
	v_lshl_add_u32 v3, v3, 2, s13
	v_lshl_add_u32 v5, v5, 2, s13
	v_lshl_add_u32 v6, v6, 2, s13
	v_lshl_add_u32 v7, v7, 2, s13
	v_lshl_add_u32 v0, v0, 2, s13
	ds_read_b32 v188, v2
	ds_read_b32 v189, v3 offset:4
	ds_read_b32 v190, v5 offset:8
	ds_read_b32 v191, v6 offset:12
	ds_read_b32 v192, v7 offset:64
	ds_read_b32 v193, v193 offset:68
	ds_read_b32 v194, v194 offset:72
	ds_read_b32 v195, v0 offset:76
	s_waitcnt lgkmcnt(4)
	v_mfma_f32_16x16x32_bf16 v[188:191], v[172:175], v[84:87], v[188:191]
	s_mov_b64 s[4:5], 0
	s_waitcnt lgkmcnt(0)
	v_mfma_f32_16x16x32_bf16 v[192:195], v[180:183], v[84:87], v[192:195]
	s_nop 0
	v_mfma_f32_16x16x32_bf16 v[188:191], v[176:179], v[88:91], v[188:191]
	v_mfma_f32_16x16x32_bf16 v[192:195], v[184:187], v[88:91], v[192:195]
	s_branch .LBB0_525

.LBB0_526:
	s_cmp_lt_u32 s20, 6
	s_mov_b64 s[4:5], -1
	s_cbranch_scc1 .Latt_plain_528
	v_lshl_add_u32 v0, s20, 6, v234
	v_max_i32_e32 v188, 0xffffffef, v0
	v_max_i32_e32 v2, 0, v0
	v_lshl_add_u32 v193, v188, 2, s13
	v_max_i32_e32 v188, 0xffffffee, v0
	v_lshl_add_u32 v2, v2, 2, s13
	v_max_i32_e32 v3, -1, v0
	v_max_i32_e32 v5, -2, v0
	v_max_i32_e32 v6, -3, v0
	v_max_i32_e32 v7, -16, v0
	v_lshl_add_u32 v194, v188, 2, s13
	v_max_i32_e32 v0, 0xffffffed, v0
	v_lshl_add_u32 v3, v3, 2, s13
	v_lshl_add_u32 v5, v5, 2, s13
	v_lshl_add_u32 v6, v6, 2, s13
	v_lshl_add_u32 v7, v7, 2, s13
	v_lshl_add_u32 v0, v0, 2, s13
	ds_read_b32 v188, v2
	ds_read_b32 v189, v3 offset:4
	ds_read_b32 v190, v5 offset:8
	ds_read_b32 v191, v6 offset:12
	ds_read_b32 v192, v7 offset:64
	ds_read_b32 v193, v193 offset:68
	ds_read_b32 v194, v194 offset:72
	ds_read_b32 v195, v0 offset:76
	s_waitcnt lgkmcnt(4)
	v_mfma_f32_16x16x32_bf16 v[188:191], v[172:175], v[92:95], v[188:191]
	s_mov_b64 s[4:5], 0
	s_waitcnt lgkmcnt(0)
	v_mfma_f32_16x16x32_bf16 v[192:195], v[180:183], v[92:95], v[192:195]
	s_nop 0
	v_mfma_f32_16x16x32_bf16 v[188:191], v[176:179], v[96:99], v[188:191]
	v_mfma_f32_16x16x32_bf16 v[192:195], v[184:187], v[96:99], v[192:195]
	s_branch .LBB0_530
.Latt_plain_528:
	s_waitcnt lgkmcnt(11)
	v_mfma_f32_16x16x32_bf16 v[172:175], v[172:175], v[92:95], v[152:155]
	s_waitcnt lgkmcnt(9)
	v_mfma_f32_16x16x32_bf16 v[152:155], v[180:183], v[92:95], v[152:155]
	s_nop 0
	v_mfma_f32_16x16x32_bf16 v[188:191], v[176:179], v[96:99], v[172:175]
	s_waitcnt lgkmcnt(8)
	v_mfma_f32_16x16x32_bf16 v[192:195], v[184:187], v[96:99], v[152:155]
